# p2_simd_balance_plus_copies
# baseline (speedup 1.0000x reference)
; __device__ __forceinline__ void mixer_prompt_run(const Args& p, int run, int c2) {
;     ...
;         const int gi = __builtin_amdgcn_readfirstlane(c2 >> 6);
;         unsigned* dst = M32 + (rowb + t0) * 512 + 256 + c2;
;         if (gi == 0) pool_prompt_w<2>(pin, t0, dst); else if (gi == 1) pool_prompt_w<4>(pin, t0, dst); else if (gi == 2) pool_prompt_w<8>(pin, t0, dst); else pool_prompt_w<16>(pin, t0, dst);
; __device__ __forceinline__ void mixer_sample_run(const Args& p, int sb, int c2) {
;     ...
;         const int w = 2 << (c2 >> 6); const float cnt = (float)w;
; __device__ __forceinline__ void p2_mixer(const Args& p, int G, int bid, int tid) {
;     const int half = __builtin_amdgcn_readfirstlane(tid >> 8), c2 = tid & 255;
;     const int vcu = (G % 8 == 0) ? (bid % 8) * (G / 8) + bid / 8 : bid;
;     for (int it = vcu; it < 512 + 64; it += G) {
;         if (it < 512) mixer_prompt_run(p, 2 * it + half, c2);
;         else mixer_sample_run(p, 2 * (it - 512) + half, c2);
;     }
.LBB0_600:
	v_and_b32_e32 v164, 0xff, v192
	v_bfe_u32 v78, v192, 8, 1
	v_mul_u32_u24_e32 v78, 0xc0, v78
	v_xor_b32_e32 v164, v164, v78
	s_lshr_b32 s41, s0, 8
	s_movk_i32 s0, 0x7f
	v_lshlrev_b32_e32 v74, 3, v164
	v_mov_b32_e32 v75, 0
	v_cmp_lt_u32_e64 s[4:5], s0, v164
	s_waitcnt lgkmcnt(0)
	v_lshl_add_u64 v[2:3], s[62:63], 0, v[74:75]
	s_mov_b64 s[0:1], 0x1000
	v_lshl_add_u64 v[4:5], v[2:3], 0, s[0:1]
	s_mov_b64 s[0:1], 0x1800
	v_lshl_add_u64 v[6:7], v[2:3], 0, s[0:1]
	s_mov_b64 s[0:1], 0x2000
	s_waitcnt vmcnt(0)
	v_lshl_add_u64 v[8:9], v[2:3], 0, s[0:1]
	s_mov_b64 s[0:1], 0x2800
	v_lshl_add_u64 v[10:11], v[2:3], 0, s[0:1]
	s_mov_b64 s[0:1], 0x3000
	v_lshl_add_u64 v[12:13], v[2:3], 0, s[0:1]
	s_mov_b64 s[0:1], 0x3800
	v_lshl_add_u64 v[14:15], v[2:3], 0, s[0:1]
	s_mov_b64 s[0:1], 0x4000
	v_lshl_add_u64 v[16:17], v[2:3], 0, s[0:1]
	s_mov_b64 s[0:1], 0x4800
	v_lshl_add_u64 v[18:19], v[2:3], 0, s[0:1]
	s_mov_b64 s[0:1], 0x5000
	v_lshl_add_u64 v[20:21], v[2:3], 0, s[0:1]
	s_mov_b64 s[0:1], 0x5800
	v_lshl_add_u64 v[22:23], v[2:3], 0, s[0:1]
	s_mov_b64 s[0:1], 0x6000
	v_lshl_add_u64 v[24:25], v[2:3], 0, s[0:1]
	s_mov_b64 s[0:1], 0x6800
	v_lshl_add_u64 v[26:27], v[2:3], 0, s[0:1]
	s_mov_b64 s[0:1], 0x7000
	v_lshl_add_u64 v[28:29], v[2:3], 0, s[0:1]
	s_mov_b64 s[0:1], 0x7800
	v_lshl_add_u64 v[30:31], v[2:3], 0, s[0:1]
	s_mov_b64 s[0:1], 0x8000
	v_lshl_add_u64 v[32:33], v[2:3], 0, s[0:1]
	s_mov_b64 s[0:1], 0x8800
	v_lshl_add_u64 v[34:35], v[2:3], 0, s[0:1]
	s_mov_b64 s[0:1], 0x9000
	v_lshl_add_u64 v[36:37], v[2:3], 0, s[0:1]
	s_mov_b64 s[0:1], 0x9800
	v_lshl_add_u64 v[38:39], v[2:3], 0, s[0:1]
	s_mov_b64 s[0:1], 0xa000
	v_lshl_add_u64 v[40:41], v[2:3], 0, s[0:1]
	s_mov_b64 s[0:1], 0xa800
	v_lshl_add_u64 v[42:43], v[2:3], 0, s[0:1]
	s_mov_b64 s[0:1], 0xb000
	v_lshl_add_u64 v[44:45], v[2:3], 0, s[0:1]
	s_mov_b64 s[0:1], 0xb800
	v_writelane_b32 v242, s92, 36
	v_lshl_add_u64 v[46:47], v[2:3], 0, s[0:1]
	s_mov_b64 s[0:1], 0xc000
	v_writelane_b32 v242, s93, 37
	v_lshl_add_u64 v[48:49], v[2:3], 0, s[0:1]
	s_mov_b64 s[0:1], 0xc800
	v_writelane_b32 v242, s88, 38
	v_lshl_add_u64 v[50:51], v[2:3], 0, s[0:1]
	s_mov_b64 s[0:1], 0xd000
	v_writelane_b32 v242, s89, 39
	v_lshl_add_u64 v[52:53], v[2:3], 0, s[0:1]
	s_mov_b64 s[0:1], 0xd800
	v_writelane_b32 v242, s90, 40
	v_lshl_add_u64 v[54:55], v[2:3], 0, s[0:1]
	s_mov_b64 s[0:1], 0xe000
	v_writelane_b32 v242, s91, 41
	v_lshl_add_u64 v[56:57], v[2:3], 0, s[0:1]
	s_mov_b64 s[0:1], 0xe800
	v_lshl_add_u64 v[58:59], v[2:3], 0, s[0:1]
	s_mov_b64 s[0:1], 0xf000
	v_lshlrev_b32_e32 v64, 2, v164
	v_mov_b32_e32 v65, v75
	v_readlane_b32 s8, v242, 19
	v_bfe_u32 v1, v192, 6, 2
	v_bfe_u32 v78, v192, 8, 1
	v_mul_u32_u24_e32 v78, 3, v78
	v_xor_b32_e32 v1, v1, v78
	v_lshl_add_u64 v[60:61], v[2:3], 0, s[0:1]
	v_lshl_add_u64 v[76:77], s[58:59], 0, v[64:65]
	s_mov_b64 s[0:1], 0x4d00000
	v_readlane_b32 s12, v242, 23
	v_readlane_b32 s13, v242, 24
	v_readlane_b32 s14, v242, 25
	v_readlane_b32 s15, v242, 26
	v_readlane_b32 s16, v242, 27
	v_readlane_b32 s17, v242, 28
	v_lshlrev_b32_e64 v0, v1, 2
	v_lshl_add_u64 v[64:65], v[76:77], 0, s[0:1]
	v_readlane_b32 s18, v242, 29
	v_readlane_b32 s19, v242, 30
	v_readlane_b32 s20, v242, 31
	v_readlane_b32 s21, v242, 32
	s_mov_b64 s[12:13], s[16:17]
	s_mov_b64 s[0:1], 0x6e00000
	v_cvt_f32_ubyte0_e32 v0, v0
	s_mov_b64 s[14:15], s[18:19]
	s_mov_b64 s[16:17], s[20:21]
	v_lshl_add_u64 v[72:73], v[76:77], 0, s[0:1]
	s_mov_b64 s[0:1], 0x5d80000
	v_mbcnt_lo_u32_b32 v78, -1, 0
	s_add_i32 s49, s41, 0xfffffc00
	v_cmp_gt_u32_e64 s[2:3], 64, v164
	v_cmp_eq_u32_e64 s[6:7], 3, v1
	v_lshl_add_u64 v[62:63], s[64:65], 0, v[74:75]
	v_lshl_add_u64 v[66:67], s[14:15], 0, v[74:75]
	v_lshl_add_u64 v[68:69], s[66:67], 0, v[74:75]
	v_lshl_add_u64 v[70:71], s[68:69], 0, v[74:75]
	v_lshl_add_u64 v[74:75], s[16:17], 0, v[74:75]
	v_lshl_add_u64 v[76:77], v[76:77], 0, s[0:1]
	v_mov_b32_e32 v1, v0
	s_mov_b32 s45, 0
	s_movk_i32 s61, 0x1000
	s_movk_i32 s90, 0x2000
	s_movk_i32 s91, 0x3000
	s_movk_i32 s82, 0x4000
	s_movk_i32 s83, 0x5000
	s_movk_i32 s95, 0x6000
	s_movk_i32 s92, 0x7000
	s_mov_b32 s48, 0x3c800000
	s_mov_b32 s60, 0x3727c5ac
	s_mov_b32 s93, 0x800000
	v_mbcnt_hi_u32_b32 v165, -1, v78
	v_mov_b32_e32 v166, 0xf000
	v_mov_b32_e32 v167, 0x7800
	v_readlane_b32 s9, v242, 20
	v_readlane_b32 s10, v242, 21
	v_readlane_b32 s11, v242, 22
	v_readlane_b32 s22, v242, 33
	v_readlane_b32 s23, v242, 34
	s_branch .LBB0_602
